# grid-barrier acquire invalidate issued at arrival (overlaps arrival atomic and the wait) instead of after release; p4 retention item-top wait counted (vmcnt 4); P1/P5 epilogue loads hoisted
# speedup vs baseline: 1.0081x; 1.0081x over previous
.LBB0_88:
	v_readlane_b32 s0, v251, 5
	s_lshl_b32 s0, s0, 8
	v_readlane_b32 s2, v251, 3
	v_readlane_b32 s3, v251, 4
	s_add_u32 s0, s2, s0
	s_addc_u32 s1, s3, 0
	v_mov_b32_e32 v1, 0x1000
	v_mov_b32_e32 v3, 1
	global_atomic_add v3, v1, v3, s[0:1] offset:1024 sc0
	buffer_inv sc1
	v_cvt_f32_u32_e32 v1, v2
	v_sub_u32_e32 v4, 0, v2
	v_rcp_iflag_f32_e32 v1, v1
	s_nop 0
	v_mul_f32_e32 v1, 0x4f7ffffe, v1
	v_cvt_u32_f32_e32 v1, v1
	v_mul_lo_u32 v4, v4, v1
	v_mul_hi_u32 v4, v1, v4
	v_add_u32_e32 v1, v1, v4
	s_waitcnt vmcnt(1)
	v_mul_hi_u32 v1, v3, v1
	v_mul_lo_u32 v4, v1, v2
	v_sub_u32_e32 v4, v3, v4
	v_add_u32_e32 v5, 1, v1
	v_cmp_ge_u32_e32 vcc, v4, v2
	v_add_u32_e32 v3, 1, v3
	s_nop 0
	v_cndmask_b32_e32 v1, v1, v5, vcc
	v_sub_u32_e32 v5, v4, v2
	v_cndmask_b32_e32 v4, v4, v5, vcc
	v_add_u32_e32 v5, 1, v1
	v_cmp_ge_u32_e32 vcc, v4, v2
	s_nop 1
	v_cndmask_b32_e32 v1, v1, v5, vcc
	v_mul_lo_u32 v4, v2, v1
	v_add_u32_e32 v2, v4, v2
	v_cmp_ne_u32_e32 vcc, v3, v2
	s_and_saveexec_b64 s[2:3], vcc
	s_xor_b64 s[8:9], exec, s[2:3]
	s_cbranch_execz .LBB0_102
	s_waitcnt lgkmcnt(0)
	v_mov_b32_e32 v0, 0x2000
	global_load_dword v0, v0, s[0:1] offset:1024 sc1
	s_add_u32 s20, s0, 0x2400
	s_addc_u32 s21, s1, 0
	s_waitcnt vmcnt(0)
	v_cmp_eq_u32_e32 vcc, v0, v1
	s_and_saveexec_b64 s[14:15], vcc
	s_cbranch_execz .LBB0_101
	s_add_u32 s18, s92, 0x2a0200
	s_addc_u32 s19, s93, 0
	s_mov_b32 s2, 1
	s_mov_b64 s[22:23], 0
	v_mov_b32_e32 v0, 0
	s_branch .LBB0_92

.LBB0_101:
	s_or_b64 exec, exec, s[14:15]
	s_waitcnt vmcnt(0)
	s_waitcnt vmcnt(0)

.LBB0_119:
	s_or_b64 exec, exec, s[8:9]
	v_mov_b32_e32 v0, 0x2000
	v_mov_b32_e32 v1, 1
	s_waitcnt vmcnt(0)
	global_atomic_add v0, v1, s[0:1] offset:1024
	s_waitcnt vmcnt(0)

.LBB0_155:
	v_readlane_b32 s2, v251, 5
	s_lshl_b32 s2, s2, 8
	v_readlane_b32 s6, v251, 3
	v_readlane_b32 s7, v251, 4
	s_add_u32 s6, s6, s2
	s_addc_u32 s7, s7, 0
	v_mov_b32_e32 v1, 0x1000
	v_mov_b32_e32 v3, 1
	v_sub_u32_e32 v4, 0, v2
	global_atomic_add v3, v1, v3, s[6:7] offset:1024 sc0
	buffer_inv sc1
	v_cvt_f32_u32_e32 v1, v2
	v_rcp_iflag_f32_e32 v1, v1
	s_nop 0
	v_mul_f32_e32 v1, 0x4f7ffffe, v1
	v_cvt_u32_f32_e32 v1, v1
	v_mul_lo_u32 v4, v4, v1
	v_mul_hi_u32 v4, v1, v4
	v_add_u32_e32 v1, v1, v4
	s_waitcnt vmcnt(1)
	v_mul_hi_u32 v1, v3, v1
	v_mul_lo_u32 v4, v1, v2
	v_sub_u32_e32 v4, v3, v4
	v_add_u32_e32 v5, 1, v1
	v_cmp_ge_u32_e32 vcc, v4, v2
	v_add_u32_e32 v3, 1, v3
	s_nop 0
	v_cndmask_b32_e32 v1, v1, v5, vcc
	v_sub_u32_e32 v5, v4, v2
	v_cndmask_b32_e32 v4, v4, v5, vcc
	v_add_u32_e32 v5, 1, v1
	v_cmp_ge_u32_e32 vcc, v4, v2
	s_nop 1
	v_cndmask_b32_e32 v1, v1, v5, vcc
	v_mul_lo_u32 v4, v2, v1
	v_add_u32_e32 v2, v4, v2
	v_cmp_ne_u32_e32 vcc, v3, v2
	s_and_saveexec_b64 s[2:3], vcc
	s_xor_b64 s[8:9], exec, s[2:3]
	s_cbranch_execz .LBB0_169
	s_waitcnt lgkmcnt(0)
	v_mov_b32_e32 v0, 0x2000
	global_load_dword v0, v0, s[6:7] offset:1024 sc1
	s_add_u32 s20, s6, 0x2400
	s_addc_u32 s21, s7, 0
	s_waitcnt vmcnt(0)
	v_cmp_eq_u32_e32 vcc, v0, v1
	s_and_saveexec_b64 s[14:15], vcc
	s_cbranch_execz .LBB0_168
	s_add_u32 s18, s92, 0x2a0200
	s_addc_u32 s19, s93, 0
	s_mov_b32 s2, 1
	s_mov_b64 s[22:23], 0
	v_mov_b32_e32 v0, 0
	s_branch .LBB0_159

.LBB0_186:
	s_or_b64 exec, exec, s[8:9]
	v_mov_b32_e32 v0, 0x2000
	v_mov_b32_e32 v1, 1
	s_waitcnt vmcnt(0)
	global_atomic_add v0, v1, s[6:7] offset:1024
	s_waitcnt vmcnt(0)

.LBB0_293:
	v_readlane_b32 s2, v251, 5
	s_lshl_b32 s2, s2, 8
	v_readlane_b32 s6, v251, 3
	v_readlane_b32 s7, v251, 4
	s_add_u32 s6, s6, s2
	s_addc_u32 s7, s7, 0
	v_mov_b32_e32 v1, 0x1000
	v_mov_b32_e32 v3, 1
	v_sub_u32_e32 v4, 0, v2
	global_atomic_add v3, v1, v3, s[6:7] offset:1024 sc0
	buffer_inv sc1
	v_cvt_f32_u32_e32 v1, v2
	v_rcp_iflag_f32_e32 v1, v1
	s_nop 0
	v_mul_f32_e32 v1, 0x4f7ffffe, v1
	v_cvt_u32_f32_e32 v1, v1
	v_mul_lo_u32 v4, v4, v1
	v_mul_hi_u32 v4, v1, v4
	v_add_u32_e32 v1, v1, v4
	s_waitcnt vmcnt(1)
	v_mul_hi_u32 v1, v3, v1
	v_mul_lo_u32 v4, v1, v2
	v_sub_u32_e32 v4, v3, v4
	v_add_u32_e32 v5, 1, v1
	v_cmp_ge_u32_e32 vcc, v4, v2
	v_add_u32_e32 v3, 1, v3
	s_nop 0
	v_cndmask_b32_e32 v1, v1, v5, vcc
	v_sub_u32_e32 v5, v4, v2
	v_cndmask_b32_e32 v4, v4, v5, vcc
	v_add_u32_e32 v5, 1, v1
	v_cmp_ge_u32_e32 vcc, v4, v2
	s_nop 1
	v_cndmask_b32_e32 v1, v1, v5, vcc
	v_mul_lo_u32 v4, v2, v1
	v_add_u32_e32 v2, v4, v2
	v_cmp_ne_u32_e32 vcc, v3, v2
	s_and_saveexec_b64 s[2:3], vcc
	s_xor_b64 s[8:9], exec, s[2:3]
	s_cbranch_execz .LBB0_307
	s_waitcnt lgkmcnt(0)
	v_mov_b32_e32 v0, 0x2000
	global_load_dword v0, v0, s[6:7] offset:1024 sc1
	s_add_u32 s14, s6, 0x2400
	s_addc_u32 s15, s7, 0
	s_waitcnt vmcnt(0)
	v_cmp_eq_u32_e32 vcc, v0, v1
	s_and_saveexec_b64 s[10:11], vcc
	s_cbranch_execz .LBB0_306
	s_add_u32 s12, s92, 0x2a0200
	s_addc_u32 s13, s93, 0
	s_mov_b32 s2, 1
	s_mov_b64 s[16:17], 0
	v_mov_b32_e32 v0, 0
	s_branch .LBB0_297

.LBB0_306:
	s_or_b64 exec, exec, s[10:11]
	s_waitcnt vmcnt(0)
	s_waitcnt vmcnt(0)

.LBB0_354:
	v_readlane_b32 s2, v251, 5
	s_lshl_b32 s2, s2, 8
	v_readlane_b32 s6, v251, 3
	v_readlane_b32 s7, v251, 4
	s_add_u32 s6, s6, s2
	s_addc_u32 s7, s7, 0
	v_mov_b32_e32 v65, 0x1000
	v_mov_b32_e32 v67, 1
	v_sub_u32_e32 v68, 0, v66
	global_atomic_add v67, v65, v67, s[6:7] offset:1024 sc0
	buffer_inv sc1
	v_cvt_f32_u32_e32 v65, v66
	v_rcp_iflag_f32_e32 v65, v65
	s_nop 0
	v_mul_f32_e32 v65, 0x4f7ffffe, v65
	v_cvt_u32_f32_e32 v65, v65
	v_mul_lo_u32 v68, v68, v65
	v_mul_hi_u32 v68, v65, v68
	v_add_u32_e32 v65, v65, v68
	s_waitcnt vmcnt(1)
	v_mul_hi_u32 v65, v67, v65
	v_mul_lo_u32 v68, v65, v66
	v_sub_u32_e32 v68, v67, v68
	v_add_u32_e32 v69, 1, v65
	v_cmp_ge_u32_e32 vcc, v68, v66
	v_add_u32_e32 v67, 1, v67
	s_nop 0
	v_cndmask_b32_e32 v65, v65, v69, vcc
	v_sub_u32_e32 v69, v68, v66
	v_cndmask_b32_e32 v68, v68, v69, vcc
	v_add_u32_e32 v69, 1, v65
	v_cmp_ge_u32_e32 vcc, v68, v66
	s_nop 1
	v_cndmask_b32_e32 v65, v65, v69, vcc
	v_mul_lo_u32 v68, v66, v65
	v_add_u32_e32 v66, v68, v66
	v_cmp_ne_u32_e32 vcc, v67, v66
	s_and_saveexec_b64 s[2:3], vcc
	s_xor_b64 s[10:11], exec, s[2:3]
	s_cbranch_execz .LBB0_368
	s_waitcnt lgkmcnt(0)
	v_mov_b32_e32 v64, 0x2000
	global_load_dword v64, v64, s[6:7] offset:1024 sc1
	s_add_u32 s16, s6, 0x2400
	s_addc_u32 s17, s7, 0
	s_waitcnt vmcnt(0)
	v_cmp_eq_u32_e32 vcc, v64, v65
	s_and_saveexec_b64 s[12:13], vcc
	s_cbranch_execz .LBB0_367
	s_add_u32 s14, s92, 0x2a0200
	s_addc_u32 s15, s93, 0
	s_mov_b32 s2, 1
	s_mov_b64 s[18:19], 0
	v_mov_b32_e32 v64, 0
	s_branch .LBB0_358

.LBB0_367:
	s_or_b64 exec, exec, s[12:13]
	s_waitcnt vmcnt(0)
	s_waitcnt vmcnt(0)

.LBB0_385:
	s_or_b64 exec, exec, s[10:11]
	v_mov_b32_e32 v64, 0x2000
	v_mov_b32_e32 v65, 1
	s_waitcnt vmcnt(0)
	global_atomic_add v64, v65, s[6:7] offset:1024
	s_waitcnt vmcnt(0)

.LBB0_394:
	s_and_b32 s41, s40, 7
	v_cvt_f32_ubyte0_e32 v64, s41
	v_sub_f32_e32 v64, 0xc0a00000, v64
	s_mov_b32 s2, 0xc2fc0000
	v_cmp_gt_f32_e32 vcc, s2, v64
	s_and_b64 s[16:17], vcc, exec
	s_cselect_b32 s2, 0xffffffc0, 0
	v_cndmask_b32_e32 v65, 0, v229, vcc
	v_add_f32_e32 v64, v64, v65
	v_exp_f32_e32 v64, v64
	s_and_b32 s42, s37, 0xffffff80
	v_add_u32_e32 v66, s42, v145
	v_cvt_f32_i32_e32 v92, v66
	v_ldexp_f32 v96, v64, s2
	v_sub_f32_e32 v97, 1.0, v96
	v_frexp_mant_f32_e32 v64, v97
	s_mov_b32 s2, 0x3f2aaaab
	v_cmp_gt_f32_e64 s[68:69], s2, v64
	s_add_i32 s2, s33, 0
	v_lshl_add_u64 v[64:65], v[134:135], 0, v[132:133]
	s_add_i32 m0, s2, 0x19800
	v_mul_f32_e32 v66, v148, v92
	global_load_lds_dwordx4 v[64:65], off
	v_lshl_add_u64 v[64:65], v[134:135], 0, v[136:137]
	s_add_i32 m0, s2, 0x1b800
	v_fract_f32_e32 v67, v66
	global_load_lds_dwordx4 v[64:65], off
	v_lshl_add_u64 v[64:65], v[134:135], 0, v[138:139]
	s_add_i32 m0, s2, 0x1d800
	v_fma_f32 v66, v92, v148, -v66
	global_load_lds_dwordx4 v[64:65], off
	v_lshl_add_u64 v[64:65], v[134:135], 0, v[140:141]
	s_add_i32 m0, s2, 0x1f800
	v_mul_f32_e32 v68, v150, v92
	global_load_lds_dwordx4 v[64:65], off
	v_mul_f32_e32 v64, v146, v92
	v_fract_f32_e32 v65, v64
	v_fma_f32 v64, v92, v146, -v64
	v_fmac_f32_e32 v64, v147, v92
	v_add_f32_e32 v64, v65, v64
	v_fmac_f32_e32 v66, v149, v92
	v_fract_f32_e32 v69, v68
	v_fma_f32 v68, v92, v150, -v68
	v_mul_f32_e32 v70, v152, v92
	v_sin_f32_e32 v65, v64
	v_cos_f32_e32 v64, v64
	v_add_f32_e32 v66, v67, v66
	v_fmac_f32_e32 v68, v151, v92
	v_fract_f32_e32 v71, v70
	v_fma_f32 v70, v92, v152, -v70
	v_mul_f32_e32 v72, v154, v92
	v_sin_f32_e32 v67, v66
	v_cos_f32_e32 v66, v66
	v_add_f32_e32 v68, v69, v68
	v_fmac_f32_e32 v70, v153, v92
	v_fract_f32_e32 v73, v72
	v_fma_f32 v72, v92, v154, -v72
	v_mul_f32_e32 v74, v156, v92
	v_sin_f32_e32 v69, v68
	v_cos_f32_e32 v68, v68
	v_add_f32_e32 v70, v71, v70
	v_fmac_f32_e32 v72, v155, v92
	v_fract_f32_e32 v75, v74
	v_fma_f32 v74, v92, v156, -v74
	v_mul_f32_e32 v76, v158, v92
	v_sin_f32_e32 v71, v70
	v_add_f32_e32 v72, v73, v72
	v_fmac_f32_e32 v74, v157, v92
	v_fract_f32_e32 v77, v76
	v_fma_f32 v76, v92, v158, -v76
	v_mul_f32_e32 v78, v160, v92
	s_waitcnt vmcnt(4)
	v_lshlrev_b32_e32 v82, 16, v16
	v_cos_f32_e32 v70, v70
	v_sin_f32_e32 v73, v72
	v_add_f32_e32 v74, v75, v74
	v_fmac_f32_e32 v76, v159, v92
	v_fract_f32_e32 v79, v78
	v_fma_f32 v78, v92, v160, -v78
	v_lshlrev_b32_e32 v80, 16, v40
	v_and_b32_e32 v83, 0xffff0000, v16
	v_mul_f32_e32 v99, v65, v82
	v_mul_f32_e32 v82, v64, v82
	v_cos_f32_e32 v72, v72
	v_sin_f32_e32 v75, v74
	v_add_f32_e32 v76, v77, v76
	v_fmac_f32_e32 v78, v161, v92
	v_and_b32_e32 v81, 0xffff0000, v40
	v_lshlrev_b32_e32 v86, 16, v17
	v_fma_f32 v99, v64, v80, -v99
	v_fmac_f32_e32 v82, v65, v80
	v_mul_f32_e32 v80, v67, v83
	v_mul_f32_e32 v83, v66, v83
	v_cos_f32_e32 v74, v74
	v_sin_f32_e32 v77, v76
	v_add_f32_e32 v78, v79, v78
	v_lshlrev_b32_e32 v84, 16, v41
	v_and_b32_e32 v87, 0xffff0000, v17
	v_fma_f32 v80, v66, v81, -v80
	v_fmac_f32_e32 v83, v67, v81
	v_mul_f32_e32 v81, v69, v86
	v_mul_f32_e32 v86, v68, v86
	v_cos_f32_e32 v76, v76
	v_sin_f32_e32 v79, v78
	v_and_b32_e32 v85, 0xffff0000, v41
	v_lshlrev_b32_e32 v90, 16, v18
	v_fma_f32 v81, v68, v84, -v81
	v_fmac_f32_e32 v86, v69, v84
	v_mul_f32_e32 v84, v71, v87
	v_cos_f32_e32 v78, v78
	v_lshlrev_b32_e32 v88, 16, v42
	v_and_b32_e32 v91, 0xffff0000, v18
	v_fma_f32 v100, v70, v85, -v84
	v_mul_f32_e32 v84, v73, v90
	v_and_b32_e32 v89, 0xffff0000, v42
	v_lshlrev_b32_e32 v95, 16, v19
	v_fma_f32 v101, v72, v88, -v84
	v_mul_f32_e32 v90, v72, v90
	v_mul_f32_e32 v84, v75, v91
	v_lshlrev_b32_e32 v93, 16, v43
	v_and_b32_e32 v98, 0xffff0000, v19
	v_mul_f32_e32 v87, v70, v87
	v_fmac_f32_e32 v90, v73, v88
	v_fma_f32 v88, v74, v89, -v84
	v_mul_f32_e32 v91, v74, v91
	v_mul_f32_e32 v84, v77, v95
	v_and_b32_e32 v94, 0xffff0000, v43
	v_fmac_f32_e32 v87, v71, v85
	v_fmac_f32_e32 v91, v75, v89
	v_fma_f32 v89, v76, v93, -v84
	v_mul_f32_e32 v95, v76, v95
	v_mul_f32_e32 v84, v79, v98
	v_fmac_f32_e32 v95, v77, v93
	v_fma_f32 v93, v78, v94, -v84
	v_cvt_pk_bf16_f32 v84, v99, v80
	v_cvt_pk_bf16_f32 v80, v82, v83
	v_cvt_pk_bf16_f32 v85, v81, v100
	v_cvt_pk_bf16_f32 v81, v86, v87
	v_cvt_pk_bf16_f32 v86, v101, v88
	v_cvt_pk_bf16_f32 v82, v90, v91
	v_cvt_pk_bf16_f32 v87, v89, v93
	v_lshlrev_b32_e32 v89, 16, v32
	v_lshlrev_b32_e32 v88, 16, v36
	v_pk_mul_f32 v[90:91], v[64:65], v[88:89]
	v_mul_f32_e32 v98, v78, v98
	v_sub_f32_e32 v90, v90, v91
	v_mul_f32_e32 v93, 0x3db504f3, v90
	v_mov_b32_e32 v90, v65
	v_mov_b32_e32 v91, v64
	v_pk_mul_f32 v[64:65], v[90:91], v[88:89]
	v_fmac_f32_e32 v98, v79, v94
	v_add_f32_e32 v64, v64, v65
	v_mul_f32_e32 v90, 0x3db504f3, v64
	v_and_b32_e32 v65, 0xffff0000, v32
	v_and_b32_e32 v64, 0xffff0000, v36
	v_pk_mul_f32 v[88:89], v[66:67], v[64:65]
	v_cvt_pk_bf16_f32 v83, v95, v98
	v_and_b32_e32 v95, 0xffff0000, v25
	v_sub_f32_e32 v88, v88, v89
	v_mul_f32_e32 v91, 0x3db504f3, v88
	v_mov_b32_e32 v88, v67
	v_mov_b32_e32 v89, v66
	v_pk_mul_f32 v[64:65], v[88:89], v[64:65]
	v_lshlrev_b32_e32 v108, 16, v26
	v_add_f32_e32 v64, v64, v65
	v_mul_f32_e32 v88, 0x3db504f3, v64
	v_lshlrev_b32_e32 v65, 16, v33
	v_lshlrev_b32_e32 v64, 16, v37
	v_pk_mul_f32 v[66:67], v[68:69], v[64:65]
	v_lshlrev_b32_e32 v106, 16, v14
	v_sub_f32_e32 v66, v66, v67
	v_mul_f32_e32 v89, 0x3db504f3, v66
	v_mov_b32_e32 v66, v69
	v_mov_b32_e32 v67, v68
	v_pk_mul_f32 v[64:65], v[66:67], v[64:65]
	v_cvt_pk_bf16_f32 v68, v93, v91
	v_and_b32_e32 v91, 0xffff0000, v24
	v_add_f32_e32 v64, v64, v65
	v_mul_f32_e32 v94, 0x3db504f3, v64
	v_and_b32_e32 v65, 0xffff0000, v33
	v_and_b32_e32 v64, 0xffff0000, v37
	v_pk_mul_f32 v[66:67], v[70:71], v[64:65]
	v_and_b32_e32 v93, 0xffff0000, v13
	v_sub_f32_e32 v66, v66, v67
	v_mul_f32_e32 v69, 0x3db504f3, v66
	v_mov_b32_e32 v66, v71
	v_mov_b32_e32 v67, v70
	v_pk_mul_f32 v[64:65], v[66:67], v[64:65]
	v_and_b32_e32 v109, 0xffff0000, v26
	v_add_f32_e32 v64, v64, v65
	v_mul_f32_e32 v70, 0x3db504f3, v64
	v_lshlrev_b32_e32 v65, 16, v34
	v_lshlrev_b32_e32 v64, 16, v38
	v_pk_mul_f32 v[66:67], v[72:73], v[64:65]
	v_and_b32_e32 v107, 0xffff0000, v14
	v_sub_f32_e32 v66, v66, v67
	v_mul_f32_e32 v71, 0x3db504f3, v66
	v_mov_b32_e32 v66, v73
	v_mov_b32_e32 v67, v72
	v_pk_mul_f32 v[64:65], v[66:67], v[64:65]
	v_lshlrev_b32_e32 v112, 16, v27
	v_add_f32_e32 v64, v64, v65
	v_mul_f32_e32 v72, 0x3db504f3, v64
	v_and_b32_e32 v65, 0xffff0000, v34
	v_and_b32_e32 v64, 0xffff0000, v38
	v_pk_mul_f32 v[66:67], v[74:75], v[64:65]
	v_lshlrev_b32_e32 v110, 16, v15
	v_sub_f32_e32 v66, v66, v67
	v_mul_f32_e32 v73, 0x3db504f3, v66
	v_mov_b32_e32 v66, v75
	v_mov_b32_e32 v67, v74
	v_pk_mul_f32 v[64:65], v[66:67], v[64:65]
	v_and_b32_e32 v113, 0xffff0000, v27
	v_add_f32_e32 v64, v64, v65
	v_mul_f32_e32 v74, 0x3db504f3, v64
	v_lshlrev_b32_e32 v65, 16, v35
	v_lshlrev_b32_e32 v64, 16, v39
	v_pk_mul_f32 v[66:67], v[76:77], v[64:65]
	v_and_b32_e32 v111, 0xffff0000, v15
	v_sub_f32_e32 v66, v66, v67
	v_mul_f32_e32 v75, 0x3db504f3, v66
	v_mov_b32_e32 v66, v77
	v_mov_b32_e32 v67, v76
	v_pk_mul_f32 v[64:65], v[66:67], v[64:65]
	s_add_i32 s40, s40, s44
	v_add_f32_e32 v64, v64, v65
	v_mul_f32_e32 v76, 0x3db504f3, v64
	v_and_b32_e32 v65, 0xffff0000, v35
	v_and_b32_e32 v64, 0xffff0000, v39
	v_pk_mul_f32 v[66:67], v[78:79], v[64:65]
	s_cmpk_gt_i32 s40, 0x1ff
	v_sub_f32_e32 v66, v66, v67
	v_mul_f32_e32 v77, 0x3db504f3, v66
	v_mov_b32_e32 v66, v79
	v_mov_b32_e32 v67, v78
	v_pk_mul_f32 v[64:65], v[66:67], v[64:65]
	v_mul_f32_e32 v78, v168, v92
	v_add_f32_e32 v64, v64, v65
	v_mul_f32_e32 v67, 0x3db504f3, v64
	v_cvt_pk_bf16_f32 v64, v90, v88
	v_mul_f32_e32 v88, v170, v92
	v_cvt_pk_bf16_f32 v69, v89, v69
	v_fract_f32_e32 v89, v88
	v_fma_f32 v88, v92, v170, -v88
	v_fmac_f32_e32 v88, v171, v92
	v_add_f32_e32 v88, v89, v88
	v_sin_f32_e32 v99, v88
	v_cos_f32_e32 v98, v88
	v_mul_f32_e32 v88, v172, v92
	v_fract_f32_e32 v89, v88
	v_fma_f32 v88, v92, v172, -v88
	v_fmac_f32_e32 v88, v173, v92
	v_add_f32_e32 v88, v89, v88
	v_cvt_pk_bf16_f32 v65, v94, v70
	v_cvt_pk_bf16_f32 v70, v71, v73
	v_cvt_pk_bf16_f32 v66, v72, v74
	v_mul_f32_e32 v72, v162, v92
	v_sin_f32_e32 v101, v88
	v_cos_f32_e32 v100, v88
	v_mul_f32_e32 v88, v174, v92
	v_fract_f32_e32 v73, v72
	v_fma_f32 v72, v92, v162, -v72
	v_mul_f32_e32 v74, v164, v92
	v_fract_f32_e32 v89, v88
	v_fma_f32 v88, v92, v174, -v88
	v_cvt_pk_bf16_f32 v71, v75, v77
	v_cvt_pk_bf16_f32 v67, v76, v67
	v_fmac_f32_e32 v72, v163, v92
	v_fract_f32_e32 v75, v74
	v_fma_f32 v74, v92, v164, -v74
	v_mul_f32_e32 v76, v166, v92
	v_fmac_f32_e32 v88, v175, v92
	v_add_f32_e32 v72, v73, v72
	v_fmac_f32_e32 v74, v165, v92
	v_fract_f32_e32 v77, v76
	v_fma_f32 v76, v92, v166, -v76
	v_add_f32_e32 v88, v89, v88
	v_sin_f32_e32 v73, v72
	v_cos_f32_e32 v72, v72
	v_add_f32_e32 v74, v75, v74
	v_fmac_f32_e32 v76, v167, v92
	v_fract_f32_e32 v79, v78
	v_fma_f32 v78, v92, v168, -v78
	v_sin_f32_e32 v103, v88
	v_cos_f32_e32 v102, v88
	v_mul_f32_e32 v88, v176, v92
	v_sin_f32_e32 v75, v74
	v_cos_f32_e32 v74, v74
	v_add_f32_e32 v76, v77, v76
	v_fmac_f32_e32 v78, v169, v92
	v_fract_f32_e32 v89, v88
	v_fma_f32 v88, v92, v176, -v88
	v_sin_f32_e32 v77, v76
	v_cos_f32_e32 v76, v76
	v_add_f32_e32 v78, v79, v78
	v_fmac_f32_e32 v88, v177, v92
	v_sin_f32_e32 v79, v78
	v_add_f32_e32 v88, v89, v88
	v_lshlrev_b32_e32 v90, 16, v24
	v_cos_f32_e32 v78, v78
	v_sin_f32_e32 v105, v88
	v_cos_f32_e32 v104, v88
	v_lshlrev_b32_e32 v88, 16, v12
	v_mul_f32_e32 v114, v73, v90
	v_mul_f32_e32 v90, v72, v90
	v_and_b32_e32 v89, 0xffff0000, v12
	v_lshlrev_b32_e32 v94, 16, v25
	v_fma_f32 v114, v72, v88, -v114
	v_fmac_f32_e32 v90, v73, v88
	v_mul_f32_e32 v88, v75, v91
	v_mul_f32_e32 v91, v74, v91
	v_lshlrev_b32_e32 v92, 16, v13
	v_fma_f32 v88, v74, v89, -v88
	v_fmac_f32_e32 v91, v75, v89
	v_mul_f32_e32 v89, v77, v94
	v_mul_f32_e32 v94, v76, v94
	v_fma_f32 v89, v76, v92, -v89
	v_fmac_f32_e32 v94, v77, v92
	v_mul_f32_e32 v92, v79, v95
	v_fma_f32 v115, v78, v93, -v92
	v_mul_f32_e32 v92, v99, v108
	v_fma_f32 v116, v98, v106, -v92
	v_mul_f32_e32 v108, v98, v108
	v_mul_f32_e32 v92, v101, v109
	v_mul_f32_e32 v95, v78, v95
	v_fmac_f32_e32 v108, v99, v106
	v_fma_f32 v106, v100, v107, -v92
	v_mul_f32_e32 v109, v100, v109
	v_mul_f32_e32 v92, v103, v112
	v_fmac_f32_e32 v95, v79, v93
	v_fmac_f32_e32 v109, v101, v107
	v_fma_f32 v107, v102, v110, -v92
	v_mul_f32_e32 v112, v102, v112
	v_mul_f32_e32 v92, v105, v113
	v_fmac_f32_e32 v112, v103, v110
	v_fma_f32 v110, v104, v111, -v92
	v_cvt_pk_bf16_f32 v92, v114, v88
	v_cvt_pk_bf16_f32 v88, v90, v91
	v_cvt_pk_bf16_f32 v93, v89, v115
	v_cvt_pk_bf16_f32 v89, v94, v95
	v_cvt_pk_bf16_f32 v94, v116, v106
	v_cvt_pk_bf16_f32 v90, v108, v109
	v_cvt_pk_bf16_f32 v95, v107, v110
	v_lshlrev_b32_e32 v107, 16, v44
	v_lshlrev_b32_e32 v106, 16, v28
	v_pk_mul_f32 v[108:109], v[72:73], v[106:107]
	v_mul_f32_e32 v113, v104, v113
	v_sub_f32_e32 v108, v108, v109
	v_mul_f32_e32 v110, 0x3db504f3, v108
	v_mov_b32_e32 v108, v73
	v_mov_b32_e32 v109, v72
	v_pk_mul_f32 v[72:73], v[108:109], v[106:107]
	v_fmac_f32_e32 v113, v105, v111
	v_add_f32_e32 v72, v72, v73
	v_mul_f32_e32 v108, 0x3db504f3, v72
	v_and_b32_e32 v73, 0xffff0000, v44
	v_and_b32_e32 v72, 0xffff0000, v28
	v_pk_mul_f32 v[106:107], v[74:75], v[72:73]
	v_cvt_pk_bf16_f32 v91, v112, v113
	s_cselect_b64 s[34:35], -1, 0
	v_sub_f32_e32 v106, v106, v107
	v_mul_f32_e32 v109, 0x3db504f3, v106
	v_mov_b32_e32 v106, v75
	v_mov_b32_e32 v107, v74
	v_pk_mul_f32 v[72:73], v[106:107], v[72:73]
	s_and_b64 vcc, exec, s[34:35]
	v_add_f32_e32 v72, v72, v73
	v_mul_f32_e32 v106, 0x3db504f3, v72
	v_lshlrev_b32_e32 v73, 16, v45
	v_lshlrev_b32_e32 v72, 16, v29
	v_pk_mul_f32 v[74:75], v[76:77], v[72:73]
	s_nop 0
	v_sub_f32_e32 v74, v74, v75
	v_mul_f32_e32 v107, 0x3db504f3, v74
	v_mov_b32_e32 v74, v77
	v_mov_b32_e32 v75, v76
	v_pk_mul_f32 v[72:73], v[74:75], v[72:73]
	s_nop 0
	v_add_f32_e32 v72, v72, v73
	v_mul_f32_e32 v77, 0x3db504f3, v72
	v_and_b32_e32 v73, 0xffff0000, v45
	v_and_b32_e32 v72, 0xffff0000, v29
	v_pk_mul_f32 v[74:75], v[78:79], v[72:73]
	s_nop 0
	v_sub_f32_e32 v74, v74, v75
	v_mul_f32_e32 v111, 0x3db504f3, v74
	v_mov_b32_e32 v74, v79
	v_mov_b32_e32 v75, v78
	v_pk_mul_f32 v[72:73], v[74:75], v[72:73]
	s_nop 0
	v_add_f32_e32 v72, v72, v73
	v_mul_f32_e32 v78, 0x3db504f3, v72
	v_lshlrev_b32_e32 v73, 16, v46
	v_lshlrev_b32_e32 v72, 16, v30
	v_pk_mul_f32 v[74:75], v[98:99], v[72:73]
	s_nop 0
	v_sub_f32_e32 v74, v74, v75
	v_mul_f32_e32 v79, 0x3db504f3, v74
	v_mov_b32_e32 v74, v99
	v_mov_b32_e32 v75, v98
	v_pk_mul_f32 v[72:73], v[74:75], v[72:73]
	s_nop 0
	v_add_f32_e32 v72, v72, v73
	v_mul_f32_e32 v98, 0x3db504f3, v72
	v_and_b32_e32 v73, 0xffff0000, v46
	v_and_b32_e32 v72, 0xffff0000, v30
	v_pk_mul_f32 v[74:75], v[100:101], v[72:73]
	s_nop 0
	v_sub_f32_e32 v74, v74, v75
	v_mul_f32_e32 v99, 0x3db504f3, v74
	v_mov_b32_e32 v74, v101
	v_mov_b32_e32 v75, v100
	v_pk_mul_f32 v[72:73], v[74:75], v[72:73]
	s_nop 0
	v_add_f32_e32 v72, v72, v73
	v_mul_f32_e32 v100, 0x3db504f3, v72
	v_lshlrev_b32_e32 v73, 16, v47
	v_lshlrev_b32_e32 v72, 16, v31
	v_pk_mul_f32 v[74:75], v[102:103], v[72:73]
	s_nop 0
	v_sub_f32_e32 v74, v74, v75
	v_mul_f32_e32 v101, 0x3db504f3, v74
	v_mov_b32_e32 v74, v103
	v_mov_b32_e32 v75, v102
	v_pk_mul_f32 v[72:73], v[74:75], v[72:73]
	s_nop 0
	v_add_f32_e32 v72, v72, v73
	v_mul_f32_e32 v102, 0x3db504f3, v72
	v_and_b32_e32 v73, 0xffff0000, v47
	v_and_b32_e32 v72, 0xffff0000, v31
	v_pk_mul_f32 v[74:75], v[104:105], v[72:73]
	s_nop 0
	v_sub_f32_e32 v74, v74, v75
	v_mul_f32_e32 v103, 0x3db504f3, v74
	v_mov_b32_e32 v74, v105
	v_mov_b32_e32 v75, v104
	v_pk_mul_f32 v[72:73], v[74:75], v[72:73]
	s_nop 0
	v_add_f32_e32 v72, v72, v73
	v_mul_f32_e32 v104, 0x3db504f3, v72
	v_cvt_pk_bf16_f32 v72, v110, v109
	v_cvt_pk_bf16_f32 v76, v108, v106
	v_cvt_pk_bf16_f32 v73, v107, v111
	v_cvt_pk_bf16_f32 v77, v77, v78
	v_cvt_pk_bf16_f32 v74, v79, v99
	v_cvt_pk_bf16_f32 v78, v98, v100
	v_cvt_pk_bf16_f32 v75, v101, v103
	v_cvt_pk_bf16_f32 v79, v102, v104
	ds_write_b128 v222, v[68:71]
	ds_write_b16 v182, v0 offset:34816
	ds_write_b16_d16_hi v182, v0 offset:35088
	ds_write_b16 v182, v1 offset:35360
	ds_write_b16_d16_hi v182, v1 offset:35632
	ds_write_b16 v182, v2 offset:35904
	ds_write_b16_d16_hi v182, v2 offset:36176
	ds_write_b16 v182, v3 offset:36448
	ds_write_b16_d16_hi v182, v3 offset:36720
	ds_write_b128 v222, v[72:75] offset:64
	ds_write_b16 v183, v4 offset:34816
	ds_write_b16_d16_hi v183, v4 offset:35088
	ds_write_b16 v182, v5 offset:44064
	ds_write_b16_d16_hi v182, v5 offset:44336
	ds_write_b16 v182, v6 offset:44608
	ds_write_b16_d16_hi v182, v6 offset:44880
	ds_write_b16 v182, v7 offset:45152
	ds_write_b16_d16_hi v182, v7 offset:45424
	ds_write_b128 v222, v[64:67] offset:128
	ds_write_b16 v182, v20 offset:52224
	ds_write_b16_d16_hi v182, v20 offset:52496
	ds_write_b16 v182, v21 offset:52768
	ds_write_b16_d16_hi v182, v21 offset:53040
	ds_write_b16 v182, v22 offset:53312
	ds_write_b16_d16_hi v182, v22 offset:53584
	ds_write_b16 v182, v23 offset:53856
	ds_write_b16_d16_hi v182, v23 offset:54128
	ds_write_b128 v222, v[76:79] offset:192
	ds_write_b16 v182, v8 offset:60928
	ds_write_b16_d16_hi v182, v8 offset:61200
	ds_write_b16 v182, v9 offset:61472
	ds_write_b16_d16_hi v182, v9 offset:61744
	ds_write_b16 v182, v10 offset:62016
	ds_write_b16_d16_hi v182, v10 offset:62288
	ds_write_b16 v182, v11 offset:62560
	ds_write_b16_d16_hi v182, v11 offset:62832
	s_waitcnt vmcnt(0)
	v_mov_b32_e32 v72, v60
	v_mov_b32_e32 v73, v61
	v_mov_b32_e32 v74, v62
	v_mov_b32_e32 v75, v63
	v_mov_b32_e32 v64, v56
	v_mov_b32_e32 v65, v57
	v_mov_b32_e32 v66, v58
	v_mov_b32_e32 v67, v59
	v_mov_b32_e32 v68, v52
	v_mov_b32_e32 v69, v53
	v_mov_b32_e32 v70, v54
	v_mov_b32_e32 v71, v55
	v_mov_b32_e32 v76, v48
	v_mov_b32_e32 v77, v49
	v_mov_b32_e32 v78, v50
	v_mov_b32_e32 v79, v51
	s_waitcnt lgkmcnt(0)
	s_barrier
	s_cbranch_vccnz .LBB0_396
	s_add_i32 s2, s36, s37
	v_readlane_b32 s16, v251, 37
	s_and_b32 s2, s2, 0xffffff80
	v_readlane_b32 s17, v251, 38
	v_add_u32_e32 v0, s2, v145
	v_mov_b32_e32 v143, v131
	v_mov_b64_e32 v[64:65], s[16:17]
	v_mad_i64_i32 v[0:1], s[16:17], v0, s97, v[64:65]
	s_and_b32 s16, s38, 0x380
	s_lshl_b32 s46, s16, 1
	v_lshl_add_u64 v[0:1], v[0:1], 0, s[46:47]
	v_lshl_add_u64 v[0:1], v[0:1], 0, v[142:143]
	v_add_co_u32_e32 v8, vcc, 0x1000, v0
	v_add_u32_e32 v66, s2, v179
	s_nop 0
	v_addc_co_u32_e32 v9, vcc, 0, v1, vcc
	v_add_co_u32_e32 v10, vcc, s3, v0
	v_mad_i64_i32 v[64:65], s[16:17], v66, s97, v[64:65]
	s_nop 0
	v_addc_co_u32_e32 v11, vcc, 0, v1, vcc
	global_load_dwordx4 v[40:43], v[8:9], off nt
	global_load_dwordx4 v[12:15], v[8:9], off offset:64 nt
	global_load_dwordx4 v[36:39], v[8:9], off offset:2048 nt
	global_load_dwordx4 v[28:31], v[8:9], off offset:2112 nt
	global_load_dwordx4 v[0:3], v[10:11], off nt
	global_load_dwordx4 v[4:7], v[10:11], off offset:64 nt
	global_load_dwordx4 v[16:19], v[8:9], off offset:128 nt
	global_load_dwordx4 v[24:27], v[8:9], off offset:192 nt
	global_load_dwordx4 v[32:35], v[8:9], off offset:2176 nt
	global_load_dwordx4 v[44:47], v[8:9], off offset:2240 nt
	global_load_dwordx4 v[20:23], v[10:11], off offset:128 nt
	s_nop 0
	global_load_dwordx4 v[8:11], v[10:11], off offset:192 nt
	v_lshl_add_u64 v[64:65], v[64:65], 0, s[46:47]
	v_lshl_add_u64 v[64:65], v[64:65], 0, v[130:131]
	s_mov_b64 s[16:17], 0x2800
	v_add_co_u32_e32 v72, vcc, s3, v64
	v_lshl_add_u64 v[76:77], v[64:65], 0, s[16:17]
	s_nop 0
	v_addc_co_u32_e32 v73, vcc, 0, v65, vcc
	global_load_dwordx4 v[64:67], v[76:77], off offset:16 nt
	global_load_dwordx4 v[68:71], v[76:77], off offset:32 nt
	s_nop 0
	global_load_dwordx4 v[72:75], v[72:73], off offset:2048 nt
	s_nop 0
	global_load_dwordx4 v[76:79], v[76:77], off offset:48 nt
